# norm waves issue their first four x rows right after the workgroup barrier at the P0->P1 global barrier entry (prologue de-serialisation)
# speedup vs baseline: 1.0031x; 1.0029x over previous
.LBB0_384:
	v_readlane_b32 s64, v254, 23
	v_readlane_b32 s66, v254, 16
	v_readlane_b32 s70, v254, 28
	v_readlane_b32 s78, v254, 30
	v_readlane_b32 s86, v254, 20
	v_readlane_b32 s87, v254, 21
	v_readlane_b32 s88, v254, 22
	v_readlane_b32 s65, v254, 24
	v_readlane_b32 s89, v254, 25
	v_readlane_b32 s67, v254, 17
	v_readlane_b32 s68, v254, 26
	v_readlane_b32 s90, v254, 27
	v_readlane_b32 s71, v254, 29
	s_mov_b64 s[96:97], s[92:93]
	v_readlane_b32 s79, v254, 31
	s_cbranch_execz .LBB0_438
	v_mbcnt_lo_u32_b32 v0, -1, 0
	v_mbcnt_hi_u32_b32 v0, -1, v0
	s_waitcnt vmcnt(0)
	s_nop 0
	v_or_b32_e32 v0, s89, v0
	v_cmp_eq_u32_e32 vcc, 0, v0
	s_barrier
	s_cmp_lt_u32 s69, 2
	s_cbranch_scc1 .Lpfx_skip
	v_readlane_b32 s5, v254, 14
	v_readlane_b32 s4, v254, 20
	v_mbcnt_lo_u32_b32 v207, -1, 0
	v_mbcnt_hi_u32_b32 v207, -1, v207
	v_lshlrev_b32_e32 v207, 4, v207
	s_mul_i32 s5, s5, 6
	s_add_i32 s5, s5, s69
	s_add_i32 s5, s5, -2
	s_and_b32 s4, s4, 7
	s_lshl_b32 s4, s4, 24
	s_add_u32 s2, s12, s4
	s_addc_u32 s3, s13, 0
	s_lshl_b32 s4, s5, 12
	s_add_u32 s2, s2, s4
	s_addc_u32 s3, s3, 0
	global_load_dwordx4 v[98:101], v207, s[2:3]
	global_load_dwordx4 v[102:105], v207, s[2:3] offset:1024
	global_load_dwordx4 v[106:109], v207, s[2:3] offset:2048
	global_load_dwordx4 v[110:113], v207, s[2:3] offset:3072
	s_add_u32 s2, s2, 0xc0000
	s_addc_u32 s3, s3, 0
	global_load_dwordx4 v[114:117], v207, s[2:3]
	global_load_dwordx4 v[118:121], v207, s[2:3] offset:1024
	global_load_dwordx4 v[122:125], v207, s[2:3] offset:2048
	global_load_dwordx4 v[126:129], v207, s[2:3] offset:3072
	s_add_u32 s2, s2, 0xc0000
	s_addc_u32 s3, s3, 0
	global_load_dwordx4 v[130:133], v207, s[2:3]
	global_load_dwordx4 v[134:137], v207, s[2:3] offset:1024
	global_load_dwordx4 v[138:141], v207, s[2:3] offset:2048
	global_load_dwordx4 v[142:145], v207, s[2:3] offset:3072
	s_add_u32 s2, s2, 0xc0000
	s_addc_u32 s3, s3, 0
	global_load_dwordx4 v[146:149], v207, s[2:3]
	global_load_dwordx4 v[150:153], v207, s[2:3] offset:1024
	global_load_dwordx4 v[154:157], v207, s[2:3] offset:2048
	global_load_dwordx4 v[158:161], v207, s[2:3] offset:3072
.Lpfx_skip:
	s_and_saveexec_b64 s[0:1], vcc
	s_cbranch_execz .LBB0_437
	s_add_i32 s2, 0, 0x22020
	v_mov_b32_e32 v0, s2
	s_waitcnt vmcnt(0) expcnt(0) lgkmcnt(0)
	ds_read_b32 v2, v0
	s_add_i32 s2, 0, 0x22024
	v_mov_b32_e32 v0, s2
	ds_read_b32 v0, v0
	s_waitcnt lgkmcnt(1)
	v_cmp_ne_u32_e32 vcc, 0, v2
	s_cbranch_vccnz .LBB0_401
	v_readlane_b32 s56, v254, 8
	v_readlane_b32 s57, v254, 9
	s_add_u32 s2, s56, 0x2200
	s_addc_u32 s3, s57, 0
	s_add_u32 s8, s56, 0x2400
	s_addc_u32 s9, s57, 0
	s_add_u32 s22, s56, 0x2500
	s_addc_u32 s23, s57, 0
	s_add_u32 s24, s56, 0x2600
	s_addc_u32 s25, s57, 0
	s_add_u32 s26, s56, 0x2700
	s_addc_u32 s27, s57, 0
	s_add_u32 s34, s56, 0x2800
	s_addc_u32 s35, s57, 0
	s_add_u32 s36, s56, 0x2900
	s_addc_u32 s37, s57, 0
	s_add_u32 s38, s56, 0x2a00
	s_addc_u32 s39, s57, 0
	s_add_u32 s40, s56, 0x2b00
	s_addc_u32 s41, s57, 0
	s_add_u32 s42, s56, 0x2c00
	s_addc_u32 s43, s57, 0
	s_add_u32 s44, s56, 0x2d00
	s_addc_u32 s45, s57, 0
	s_add_u32 s46, s56, 0x2e00
	s_addc_u32 s47, s57, 0
	s_add_u32 s48, s56, 0x2f00
	s_addc_u32 s49, s57, 0
	s_add_u32 s50, s56, 0x3000
	s_addc_u32 s51, s57, 0
	s_add_u32 s52, s56, 0x3100
	s_addc_u32 s53, s57, 0
	s_add_u32 s54, s56, 0x3200
	s_addc_u32 s55, s57, 0
	s_add_u32 s56, s56, 0x3300
	s_addc_u32 s57, s57, 0
	s_mov_b32 s10, 1
	v_mov_b32_e32 v16, 0
	v_readlane_b32 s58, v254, 10
	v_readlane_b32 s59, v254, 11
	s_branch .LBB0_389

.LBB0_441:
	s_waitcnt lgkmcnt(0)
	s_cmp_lt_u32 s69, 2
	s_cbranch_scc1 .LBB0_443
	v_mbcnt_lo_u32_b32 v207, -1, 0
	v_mbcnt_hi_u32_b32 v207, -1, v207
	v_lshlrev_b32_e32 v208, 3, v207
	v_lshlrev_b32_e32 v207, 4, v207
	v_mov_b32_e32 v206, 0x358637bd
	s_mov_b32 s22, 0x3a800000
	v_readlane_b32 s5, v254, 14
	v_readlane_b32 s2, v254, 8
	v_readlane_b32 s3, v254, 9
	s_mul_i32 s5, s5, 6
	s_add_i32 s5, s5, s69
	s_add_i32 s5, s5, -2
	s_cmp_lt_u32 s5, 64
	s_cselect_b32 s23, 0xc0000, 0
	s_cselect_b32 s28, 0x60000, 0
	s_lshl_b32 s4, s78, 24
	s_add_u32 s0, s12, s4
	s_addc_u32 s1, s13, 0
	s_lshl_b32 s4, s5, 12
	s_add_u32 s0, s0, s4
	s_addc_u32 s1, s1, 0
	s_add_u32 s0, s0, 0x300000
	s_addc_u32 s1, s1, 0
	s_add_u32 s2, s2, 0x4000000
	s_addc_u32 s3, s3, 0
	s_lshl_b32 s4, s78, 23
	s_add_u32 s2, s2, s4
	s_addc_u32 s3, s3, 0
	s_lshl_b32 s4, s5, 11
	s_add_u32 s2, s2, s4
	s_addc_u32 s3, s3, 0
	s_mul_i32 s4, s78, 0x12000
	s_add_u32 s8, s64, s4
	s_addc_u32 s9, s65, 0
	global_load_dwordx4 v[178:181], v207, s[8:9]
	global_load_dwordx4 v[182:185], v207, s[8:9] offset:1024
	global_load_dwordx4 v[186:189], v207, s[8:9] offset:2048
	global_load_dwordx4 v[190:193], v207, s[8:9] offset:3072
	s_add_u32 s8, s8, 0x1000
	s_addc_u32 s9, s9, 0
	global_load_dwordx4 v[162:165], v207, s[8:9]
	global_load_dwordx4 v[166:169], v207, s[8:9] offset:1024
	global_load_dwordx4 v[170:173], v207, s[8:9] offset:2048
	global_load_dwordx4 v[174:177], v207, s[8:9] offset:3072
	s_add_u32 s8, s8, 0x8000
	s_addc_u32 s9, s9, 0
	global_load_dwordx4 v[238:241], v207, s[8:9]
	global_load_dwordx4 v[242:245], v207, s[8:9] offset:1024
	global_load_dwordx4 v[246:249], v207, s[8:9] offset:2048
	global_load_dwordx4 v[250:253], v207, s[8:9] offset:3072
	s_add_u32 s8, s8, 0x1000
	s_addc_u32 s9, s9, 0
	global_load_dwordx4 v[222:225], v207, s[8:9]
	global_load_dwordx4 v[226:229], v207, s[8:9] offset:1024
	global_load_dwordx4 v[230:233], v207, s[8:9] offset:2048
	global_load_dwordx4 v[234:237], v207, s[8:9] offset:3072
	s_waitcnt vmcnt(24)
	s_waitcnt vmcnt(8)
	v_mul_f32_e32 v194, v98, v98
	v_mul_f32_e32 v195, v102, v102
	v_mul_f32_e32 v196, v106, v106
	v_mul_f32_e32 v197, v110, v110
	v_mul_f32_e32 v198, v114, v114
	v_mul_f32_e32 v199, v118, v118
	v_mul_f32_e32 v200, v122, v122
	v_mul_f32_e32 v201, v126, v126
	v_fmac_f32_e32 v194, v99, v99
	v_fmac_f32_e32 v195, v103, v103
	v_fmac_f32_e32 v196, v107, v107
	v_fmac_f32_e32 v197, v111, v111
	v_fmac_f32_e32 v198, v115, v115
	v_fmac_f32_e32 v199, v119, v119
	v_fmac_f32_e32 v200, v123, v123
	v_fmac_f32_e32 v201, v127, v127
	v_fmac_f32_e32 v194, v100, v100
	v_fmac_f32_e32 v195, v104, v104
	v_fmac_f32_e32 v196, v108, v108
	v_fmac_f32_e32 v197, v112, v112
	v_fmac_f32_e32 v198, v116, v116
	v_fmac_f32_e32 v199, v120, v120
	v_fmac_f32_e32 v200, v124, v124
	v_fmac_f32_e32 v201, v128, v128
	v_fmac_f32_e32 v194, v101, v101
	v_fmac_f32_e32 v195, v105, v105
	v_fmac_f32_e32 v196, v109, v109
	v_fmac_f32_e32 v197, v113, v113
	v_fmac_f32_e32 v198, v117, v117
	v_fmac_f32_e32 v199, v121, v121
	v_fmac_f32_e32 v200, v125, v125
	v_fmac_f32_e32 v201, v129, v129
	v_add_f32_e32 v194, v194, v195
	v_add_f32_e32 v196, v196, v197
	v_add_f32_e32 v198, v198, v199
	v_add_f32_e32 v200, v200, v201
	v_add_f32_e32 v202, v194, v196
	v_add_f32_e32 v203, v198, v200
	s_nop 0
	v_add_f32_dpp v202, v202, v202 quad_perm:[1,0,3,2] row_mask:0xf bank_mask:0xf
	v_add_f32_dpp v203, v203, v203 quad_perm:[1,0,3,2] row_mask:0xf bank_mask:0xf
	s_nop 0
	v_add_f32_dpp v202, v202, v202 quad_perm:[2,3,0,1] row_mask:0xf bank_mask:0xf
	v_add_f32_dpp v203, v203, v203 quad_perm:[2,3,0,1] row_mask:0xf bank_mask:0xf
	s_nop 0
	v_add_f32_dpp v202, v202, v202 row_half_mirror row_mask:0xf bank_mask:0xf
	v_add_f32_dpp v203, v203, v203 row_half_mirror row_mask:0xf bank_mask:0xf
	s_nop 0
	v_add_f32_dpp v202, v202, v202 row_mirror row_mask:0xf bank_mask:0xf
	v_add_f32_dpp v203, v203, v203 row_mirror row_mask:0xf bank_mask:0xf
	s_nop 0
	v_add_f32_dpp v202, v202, v202 row_bcast:15 row_mask:0xa bank_mask:0xf
	v_add_f32_dpp v203, v203, v203 row_bcast:15 row_mask:0xa bank_mask:0xf
	s_nop 0
	v_add_f32_dpp v202, v202, v202 row_bcast:31 row_mask:0xc bank_mask:0xf
	v_add_f32_dpp v203, v203, v203 row_bcast:31 row_mask:0xc bank_mask:0xf
	s_nop 0
	v_fma_f32 v202, v202, s22, v206
	v_fma_f32 v203, v203, s22, v206
	v_rsq_f32_e32 v202, v202
	v_rsq_f32_e32 v203, v203
	s_nop 0
	v_readlane_b32 s10, v202, 63
	v_readlane_b32 s11, v203, 63
	s_nop 1
	v_mul_f32_e32 v204, s10, v98
	v_fma_f32 v98, v204, v162, v178
	v_mul_f32_e32 v205, s10, v99
	v_fma_f32 v99, v205, v163, v179
	v_mul_f32_e32 v204, s10, v100
	v_fma_f32 v100, v204, v164, v180
	v_mul_f32_e32 v205, s10, v101
	v_fma_f32 v101, v205, v165, v181
	v_mul_f32_e32 v204, s10, v102
	v_fma_f32 v102, v204, v166, v182
	v_mul_f32_e32 v205, s10, v103
	v_fma_f32 v103, v205, v167, v183
	v_mul_f32_e32 v204, s10, v104
	v_fma_f32 v104, v204, v168, v184
	v_mul_f32_e32 v205, s10, v105
	v_fma_f32 v105, v205, v169, v185
	v_mul_f32_e32 v204, s10, v106
	v_fma_f32 v106, v204, v170, v186
	v_mul_f32_e32 v205, s10, v107
	v_fma_f32 v107, v205, v171, v187
	v_mul_f32_e32 v204, s10, v108
	v_fma_f32 v108, v204, v172, v188
	v_mul_f32_e32 v205, s10, v109
	v_fma_f32 v109, v205, v173, v189
	v_mul_f32_e32 v204, s10, v110
	v_fma_f32 v110, v204, v174, v190
	v_mul_f32_e32 v205, s10, v111
	v_fma_f32 v111, v205, v175, v191
	v_mul_f32_e32 v204, s10, v112
	v_fma_f32 v112, v204, v176, v192
	v_mul_f32_e32 v205, s10, v113
	v_fma_f32 v113, v205, v177, v193
	v_cvt_pk_bf16_f32 v214, v98, v99
	v_cvt_pk_bf16_f32 v215, v100, v101
	v_cvt_pk_bf16_f32 v216, v102, v103
	v_cvt_pk_bf16_f32 v217, v104, v105
	v_cvt_pk_bf16_f32 v218, v106, v107
	v_cvt_pk_bf16_f32 v219, v108, v109
	v_cvt_pk_bf16_f32 v220, v110, v111
	v_cvt_pk_bf16_f32 v221, v112, v113
	global_store_dwordx2 v208, v[214:215], s[2:3]
	global_store_dwordx2 v208, v[216:217], s[2:3] offset:512
	global_store_dwordx2 v208, v[218:219], s[2:3] offset:1024
	global_store_dwordx2 v208, v[220:221], s[2:3] offset:1536
	s_add_u32 s2, s2, 0x60000
	s_addc_u32 s3, s3, 0
	v_mul_f32_e32 v204, s11, v114
	v_fma_f32 v114, v204, v162, v178
	v_mul_f32_e32 v205, s11, v115
	v_fma_f32 v115, v205, v163, v179
	v_mul_f32_e32 v204, s11, v116
	v_fma_f32 v116, v204, v164, v180
	v_mul_f32_e32 v205, s11, v117
	v_fma_f32 v117, v205, v165, v181
	v_mul_f32_e32 v204, s11, v118
	v_fma_f32 v118, v204, v166, v182
	v_mul_f32_e32 v205, s11, v119
	v_fma_f32 v119, v205, v167, v183
	v_mul_f32_e32 v204, s11, v120
	v_fma_f32 v120, v204, v168, v184
	v_mul_f32_e32 v205, s11, v121
	v_fma_f32 v121, v205, v169, v185
	v_mul_f32_e32 v204, s11, v122
	v_fma_f32 v122, v204, v170, v186
	v_mul_f32_e32 v205, s11, v123
	v_fma_f32 v123, v205, v171, v187
	v_mul_f32_e32 v204, s11, v124
	v_fma_f32 v124, v204, v172, v188
	v_mul_f32_e32 v205, s11, v125
	v_fma_f32 v125, v205, v173, v189
	v_mul_f32_e32 v204, s11, v126
	v_fma_f32 v126, v204, v174, v190
	v_mul_f32_e32 v205, s11, v127
	v_fma_f32 v127, v205, v175, v191
	v_mul_f32_e32 v204, s11, v128
	v_fma_f32 v128, v204, v176, v192
	v_mul_f32_e32 v205, s11, v129
	v_fma_f32 v129, v205, v177, v193
	v_cvt_pk_bf16_f32 v40, v114, v115
	v_cvt_pk_bf16_f32 v41, v116, v117
	v_cvt_pk_bf16_f32 v42, v118, v119
	v_cvt_pk_bf16_f32 v43, v120, v121
	v_cvt_pk_bf16_f32 v44, v122, v123
	v_cvt_pk_bf16_f32 v45, v124, v125
	v_cvt_pk_bf16_f32 v46, v126, v127
	v_cvt_pk_bf16_f32 v47, v128, v129
	global_store_dwordx2 v208, v[40:41], s[2:3]
	global_store_dwordx2 v208, v[42:43], s[2:3] offset:512
	global_store_dwordx2 v208, v[44:45], s[2:3] offset:1024
	global_store_dwordx2 v208, v[46:47], s[2:3] offset:1536
	s_add_u32 s2, s2, 0x60000
	s_addc_u32 s3, s3, 0
	global_load_dwordx4 v[98:101], v207, s[0:1]
	global_load_dwordx4 v[102:105], v207, s[0:1] offset:1024
	global_load_dwordx4 v[106:109], v207, s[0:1] offset:2048
	global_load_dwordx4 v[110:113], v207, s[0:1] offset:3072
	s_add_u32 s0, s0, 0xc0000
	s_addc_u32 s1, s1, 0
	global_load_dwordx4 v[114:117], v207, s[0:1]
	global_load_dwordx4 v[118:121], v207, s[0:1] offset:1024
	global_load_dwordx4 v[122:125], v207, s[0:1] offset:2048
	global_load_dwordx4 v[126:129], v207, s[0:1] offset:3072
	s_add_u32 s0, s0, 0xc0000
	s_addc_u32 s1, s1, 0
	s_waitcnt vmcnt(32)
	v_mul_f32_e32 v194, v130, v130
	v_mul_f32_e32 v195, v134, v134
	v_mul_f32_e32 v196, v138, v138
	v_mul_f32_e32 v197, v142, v142
	v_mul_f32_e32 v198, v146, v146
	v_mul_f32_e32 v199, v150, v150
	v_mul_f32_e32 v200, v154, v154
	v_mul_f32_e32 v201, v158, v158
	v_fmac_f32_e32 v194, v131, v131
	v_fmac_f32_e32 v195, v135, v135
	v_fmac_f32_e32 v196, v139, v139
	v_fmac_f32_e32 v197, v143, v143
	v_fmac_f32_e32 v198, v147, v147
	v_fmac_f32_e32 v199, v151, v151
	v_fmac_f32_e32 v200, v155, v155
	v_fmac_f32_e32 v201, v159, v159
	v_fmac_f32_e32 v194, v132, v132
	v_fmac_f32_e32 v195, v136, v136
	v_fmac_f32_e32 v196, v140, v140
	v_fmac_f32_e32 v197, v144, v144
	v_fmac_f32_e32 v198, v148, v148
	v_fmac_f32_e32 v199, v152, v152
	v_fmac_f32_e32 v200, v156, v156
	v_fmac_f32_e32 v201, v160, v160
	v_fmac_f32_e32 v194, v133, v133
	v_fmac_f32_e32 v195, v137, v137
	v_fmac_f32_e32 v196, v141, v141
	v_fmac_f32_e32 v197, v145, v145
	v_fmac_f32_e32 v198, v149, v149
	v_fmac_f32_e32 v199, v153, v153
	v_fmac_f32_e32 v200, v157, v157
	v_fmac_f32_e32 v201, v161, v161
	v_add_f32_e32 v194, v194, v195
	v_add_f32_e32 v196, v196, v197
	v_add_f32_e32 v198, v198, v199
	v_add_f32_e32 v200, v200, v201
	v_add_f32_e32 v202, v194, v196
	v_add_f32_e32 v203, v198, v200
	s_nop 0
	v_add_f32_dpp v202, v202, v202 quad_perm:[1,0,3,2] row_mask:0xf bank_mask:0xf
	v_add_f32_dpp v203, v203, v203 quad_perm:[1,0,3,2] row_mask:0xf bank_mask:0xf
	s_nop 0
	v_add_f32_dpp v202, v202, v202 quad_perm:[2,3,0,1] row_mask:0xf bank_mask:0xf
	v_add_f32_dpp v203, v203, v203 quad_perm:[2,3,0,1] row_mask:0xf bank_mask:0xf
	s_nop 0
	v_add_f32_dpp v202, v202, v202 row_half_mirror row_mask:0xf bank_mask:0xf
	v_add_f32_dpp v203, v203, v203 row_half_mirror row_mask:0xf bank_mask:0xf
	s_nop 0
	v_add_f32_dpp v202, v202, v202 row_mirror row_mask:0xf bank_mask:0xf
	v_add_f32_dpp v203, v203, v203 row_mirror row_mask:0xf bank_mask:0xf
	s_nop 0
	v_add_f32_dpp v202, v202, v202 row_bcast:15 row_mask:0xa bank_mask:0xf
	v_add_f32_dpp v203, v203, v203 row_bcast:15 row_mask:0xa bank_mask:0xf
	s_nop 0
	v_add_f32_dpp v202, v202, v202 row_bcast:31 row_mask:0xc bank_mask:0xf
	v_add_f32_dpp v203, v203, v203 row_bcast:31 row_mask:0xc bank_mask:0xf
	s_nop 0
	v_fma_f32 v202, v202, s22, v206
	v_fma_f32 v203, v203, s22, v206
	v_rsq_f32_e32 v202, v202
	v_rsq_f32_e32 v203, v203
	s_nop 0
	v_readlane_b32 s10, v202, 63
	v_readlane_b32 s11, v203, 63
	s_nop 1
	v_mul_f32_e32 v204, s10, v130
	v_fma_f32 v130, v204, v162, v178
	v_mul_f32_e32 v205, s10, v131
	v_fma_f32 v131, v205, v163, v179
	v_mul_f32_e32 v204, s10, v132
	v_fma_f32 v132, v204, v164, v180
	v_mul_f32_e32 v205, s10, v133
	v_fma_f32 v133, v205, v165, v181
	v_mul_f32_e32 v204, s10, v134
	v_fma_f32 v134, v204, v166, v182
	v_mul_f32_e32 v205, s10, v135
	v_fma_f32 v135, v205, v167, v183
	v_mul_f32_e32 v204, s10, v136
	v_fma_f32 v136, v204, v168, v184
	v_mul_f32_e32 v205, s10, v137
	v_fma_f32 v137, v205, v169, v185
	v_mul_f32_e32 v204, s10, v138
	v_fma_f32 v138, v204, v170, v186
	v_mul_f32_e32 v205, s10, v139
	v_fma_f32 v139, v205, v171, v187
	v_mul_f32_e32 v204, s10, v140
	v_fma_f32 v140, v204, v172, v188
	v_mul_f32_e32 v205, s10, v141
	v_fma_f32 v141, v205, v173, v189
	v_mul_f32_e32 v204, s10, v142
	v_fma_f32 v142, v204, v174, v190
	v_mul_f32_e32 v205, s10, v143
	v_fma_f32 v143, v205, v175, v191
	v_mul_f32_e32 v204, s10, v144
	v_fma_f32 v144, v204, v176, v192
	v_mul_f32_e32 v205, s10, v145
	v_fma_f32 v145, v205, v177, v193
	v_cvt_pk_bf16_f32 v214, v130, v131
	v_cvt_pk_bf16_f32 v215, v132, v133
	v_cvt_pk_bf16_f32 v216, v134, v135
	v_cvt_pk_bf16_f32 v217, v136, v137
	v_cvt_pk_bf16_f32 v218, v138, v139
	v_cvt_pk_bf16_f32 v219, v140, v141
	v_cvt_pk_bf16_f32 v220, v142, v143
	v_cvt_pk_bf16_f32 v221, v144, v145
	global_store_dwordx2 v208, v[214:215], s[2:3]
	global_store_dwordx2 v208, v[216:217], s[2:3] offset:512
	global_store_dwordx2 v208, v[218:219], s[2:3] offset:1024
	global_store_dwordx2 v208, v[220:221], s[2:3] offset:1536
	s_add_u32 s2, s2, 0x60000
	s_addc_u32 s3, s3, 0
	v_mul_f32_e32 v204, s11, v146
	v_fma_f32 v146, v204, v162, v178
	v_mul_f32_e32 v205, s11, v147
	v_fma_f32 v147, v205, v163, v179
	v_mul_f32_e32 v204, s11, v148
	v_fma_f32 v148, v204, v164, v180
	v_mul_f32_e32 v205, s11, v149
	v_fma_f32 v149, v205, v165, v181
	v_mul_f32_e32 v204, s11, v150
	v_fma_f32 v150, v204, v166, v182
	v_mul_f32_e32 v205, s11, v151
	v_fma_f32 v151, v205, v167, v183
	v_mul_f32_e32 v204, s11, v152
	v_fma_f32 v152, v204, v168, v184
	v_mul_f32_e32 v205, s11, v153
	v_fma_f32 v153, v205, v169, v185
	v_mul_f32_e32 v204, s11, v154
	v_fma_f32 v154, v204, v170, v186
	v_mul_f32_e32 v205, s11, v155
	v_fma_f32 v155, v205, v171, v187
	v_mul_f32_e32 v204, s11, v156
	v_fma_f32 v156, v204, v172, v188
	v_mul_f32_e32 v205, s11, v157
	v_fma_f32 v157, v205, v173, v189
	v_mul_f32_e32 v204, s11, v158
	v_fma_f32 v158, v204, v174, v190
	v_mul_f32_e32 v205, s11, v159
	v_fma_f32 v159, v205, v175, v191
	v_mul_f32_e32 v204, s11, v160
	v_fma_f32 v160, v204, v176, v192
	v_mul_f32_e32 v205, s11, v161
	v_fma_f32 v161, v205, v177, v193
	v_cvt_pk_bf16_f32 v40, v146, v147
	v_cvt_pk_bf16_f32 v41, v148, v149
	v_cvt_pk_bf16_f32 v42, v150, v151
	v_cvt_pk_bf16_f32 v43, v152, v153
	v_cvt_pk_bf16_f32 v44, v154, v155
	v_cvt_pk_bf16_f32 v45, v156, v157
	v_cvt_pk_bf16_f32 v46, v158, v159
	v_cvt_pk_bf16_f32 v47, v160, v161
	global_store_dwordx2 v208, v[40:41], s[2:3]
	global_store_dwordx2 v208, v[42:43], s[2:3] offset:512
	global_store_dwordx2 v208, v[44:45], s[2:3] offset:1024
	global_store_dwordx2 v208, v[46:47], s[2:3] offset:1536
	s_add_u32 s2, s2, 0x60000
	s_addc_u32 s3, s3, 0
	global_load_dwordx4 v[130:133], v207, s[0:1]
	global_load_dwordx4 v[134:137], v207, s[0:1] offset:1024
	global_load_dwordx4 v[138:141], v207, s[0:1] offset:2048
	global_load_dwordx4 v[142:145], v207, s[0:1] offset:3072
	s_add_u32 s0, s0, 0xc0000
	s_addc_u32 s1, s1, 0
	global_load_dwordx4 v[146:149], v207, s[0:1]
	global_load_dwordx4 v[150:153], v207, s[0:1] offset:1024
	global_load_dwordx4 v[154:157], v207, s[0:1] offset:2048
	global_load_dwordx4 v[158:161], v207, s[0:1] offset:3072
	s_add_u32 s0, s0, 0xc0000
	s_addc_u32 s1, s1, 0
	s_waitcnt vmcnt(16)
	v_mul_f32_e32 v194, v98, v98
	v_mul_f32_e32 v195, v102, v102
	v_mul_f32_e32 v196, v106, v106
	v_mul_f32_e32 v197, v110, v110
	v_mul_f32_e32 v198, v114, v114
	v_mul_f32_e32 v199, v118, v118
	v_mul_f32_e32 v200, v122, v122
	v_mul_f32_e32 v201, v126, v126
	v_fmac_f32_e32 v194, v99, v99
	v_fmac_f32_e32 v195, v103, v103
	v_fmac_f32_e32 v196, v107, v107
	v_fmac_f32_e32 v197, v111, v111
	v_fmac_f32_e32 v198, v115, v115
	v_fmac_f32_e32 v199, v119, v119
	v_fmac_f32_e32 v200, v123, v123
	v_fmac_f32_e32 v201, v127, v127
	v_fmac_f32_e32 v194, v100, v100
	v_fmac_f32_e32 v195, v104, v104
	v_fmac_f32_e32 v196, v108, v108
	v_fmac_f32_e32 v197, v112, v112
	v_fmac_f32_e32 v198, v116, v116
	v_fmac_f32_e32 v199, v120, v120
	v_fmac_f32_e32 v200, v124, v124
	v_fmac_f32_e32 v201, v128, v128
	v_fmac_f32_e32 v194, v101, v101
	v_fmac_f32_e32 v195, v105, v105
	v_fmac_f32_e32 v196, v109, v109
	v_fmac_f32_e32 v197, v113, v113
	v_fmac_f32_e32 v198, v117, v117
	v_fmac_f32_e32 v199, v121, v121
	v_fmac_f32_e32 v200, v125, v125
	v_fmac_f32_e32 v201, v129, v129
	v_add_f32_e32 v194, v194, v195
	v_add_f32_e32 v196, v196, v197
	v_add_f32_e32 v198, v198, v199
	v_add_f32_e32 v200, v200, v201
	v_add_f32_e32 v202, v194, v196
	v_add_f32_e32 v203, v198, v200
	s_nop 0
	v_add_f32_dpp v202, v202, v202 quad_perm:[1,0,3,2] row_mask:0xf bank_mask:0xf
	v_add_f32_dpp v203, v203, v203 quad_perm:[1,0,3,2] row_mask:0xf bank_mask:0xf
	s_nop 0
	v_add_f32_dpp v202, v202, v202 quad_perm:[2,3,0,1] row_mask:0xf bank_mask:0xf
	v_add_f32_dpp v203, v203, v203 quad_perm:[2,3,0,1] row_mask:0xf bank_mask:0xf
	s_nop 0
	v_add_f32_dpp v202, v202, v202 row_half_mirror row_mask:0xf bank_mask:0xf
	v_add_f32_dpp v203, v203, v203 row_half_mirror row_mask:0xf bank_mask:0xf
	s_nop 0
	v_add_f32_dpp v202, v202, v202 row_mirror row_mask:0xf bank_mask:0xf
	v_add_f32_dpp v203, v203, v203 row_mirror row_mask:0xf bank_mask:0xf
	s_nop 0
	v_add_f32_dpp v202, v202, v202 row_bcast:15 row_mask:0xa bank_mask:0xf
	v_add_f32_dpp v203, v203, v203 row_bcast:15 row_mask:0xa bank_mask:0xf
	s_nop 0
	v_add_f32_dpp v202, v202, v202 row_bcast:31 row_mask:0xc bank_mask:0xf
	v_add_f32_dpp v203, v203, v203 row_bcast:31 row_mask:0xc bank_mask:0xf
	s_nop 0
	v_fma_f32 v202, v202, s22, v206
	v_fma_f32 v203, v203, s22, v206
	v_rsq_f32_e32 v202, v202
	v_rsq_f32_e32 v203, v203
	s_nop 0
	v_readlane_b32 s10, v202, 63
	v_readlane_b32 s11, v203, 63
	s_nop 1
	v_mul_f32_e32 v204, s10, v98
	v_fma_f32 v98, v204, v162, v178
	v_mul_f32_e32 v205, s10, v99
	v_fma_f32 v99, v205, v163, v179
	v_mul_f32_e32 v204, s10, v100
	v_fma_f32 v100, v204, v164, v180
	v_mul_f32_e32 v205, s10, v101
	v_fma_f32 v101, v205, v165, v181
	v_mul_f32_e32 v204, s10, v102
	v_fma_f32 v102, v204, v166, v182
	v_mul_f32_e32 v205, s10, v103
	v_fma_f32 v103, v205, v167, v183
	v_mul_f32_e32 v204, s10, v104
	v_fma_f32 v104, v204, v168, v184
	v_mul_f32_e32 v205, s10, v105
	v_fma_f32 v105, v205, v169, v185
	v_mul_f32_e32 v204, s10, v106
	v_fma_f32 v106, v204, v170, v186
	v_mul_f32_e32 v205, s10, v107
	v_fma_f32 v107, v205, v171, v187
	v_mul_f32_e32 v204, s10, v108
	v_fma_f32 v108, v204, v172, v188
	v_mul_f32_e32 v205, s10, v109
	v_fma_f32 v109, v205, v173, v189
	v_mul_f32_e32 v204, s10, v110
	v_fma_f32 v110, v204, v174, v190
	v_mul_f32_e32 v205, s10, v111
	v_fma_f32 v111, v205, v175, v191
	v_mul_f32_e32 v204, s10, v112
	v_fma_f32 v112, v204, v176, v192
	v_mul_f32_e32 v205, s10, v113
	v_fma_f32 v113, v205, v177, v193
	v_cvt_pk_bf16_f32 v214, v98, v99
	v_cvt_pk_bf16_f32 v215, v100, v101
	v_cvt_pk_bf16_f32 v216, v102, v103
	v_cvt_pk_bf16_f32 v217, v104, v105
	v_cvt_pk_bf16_f32 v218, v106, v107
	v_cvt_pk_bf16_f32 v219, v108, v109
	v_cvt_pk_bf16_f32 v220, v110, v111
	v_cvt_pk_bf16_f32 v221, v112, v113
	global_store_dwordx2 v208, v[214:215], s[2:3]
	global_store_dwordx2 v208, v[216:217], s[2:3] offset:512
	global_store_dwordx2 v208, v[218:219], s[2:3] offset:1024
	global_store_dwordx2 v208, v[220:221], s[2:3] offset:1536
	s_add_u32 s2, s2, 0x60000
	s_addc_u32 s3, s3, 0
	v_mul_f32_e32 v204, s11, v114
	v_fma_f32 v114, v204, v162, v178
	v_mul_f32_e32 v205, s11, v115
	v_fma_f32 v115, v205, v163, v179
	v_mul_f32_e32 v204, s11, v116
	v_fma_f32 v116, v204, v164, v180
	v_mul_f32_e32 v205, s11, v117
	v_fma_f32 v117, v205, v165, v181
	v_mul_f32_e32 v204, s11, v118
	v_fma_f32 v118, v204, v166, v182
	v_mul_f32_e32 v205, s11, v119
	v_fma_f32 v119, v205, v167, v183
	v_mul_f32_e32 v204, s11, v120
	v_fma_f32 v120, v204, v168, v184
	v_mul_f32_e32 v205, s11, v121
	v_fma_f32 v121, v205, v169, v185
	v_mul_f32_e32 v204, s11, v122
	v_fma_f32 v122, v204, v170, v186
	v_mul_f32_e32 v205, s11, v123
	v_fma_f32 v123, v205, v171, v187
	v_mul_f32_e32 v204, s11, v124
	v_fma_f32 v124, v204, v172, v188
	v_mul_f32_e32 v205, s11, v125
	v_fma_f32 v125, v205, v173, v189
	v_mul_f32_e32 v204, s11, v126
	v_fma_f32 v126, v204, v174, v190
	v_mul_f32_e32 v205, s11, v127
	v_fma_f32 v127, v205, v175, v191
	v_mul_f32_e32 v204, s11, v128
	v_fma_f32 v128, v204, v176, v192
	v_mul_f32_e32 v205, s11, v129
	v_fma_f32 v129, v205, v177, v193
	v_cvt_pk_bf16_f32 v40, v114, v115
	v_cvt_pk_bf16_f32 v41, v116, v117
	v_cvt_pk_bf16_f32 v42, v118, v119
	v_cvt_pk_bf16_f32 v43, v120, v121
	v_cvt_pk_bf16_f32 v44, v122, v123
	v_cvt_pk_bf16_f32 v45, v124, v125
	v_cvt_pk_bf16_f32 v46, v126, v127
	v_cvt_pk_bf16_f32 v47, v128, v129
	global_store_dwordx2 v208, v[40:41], s[2:3]
	global_store_dwordx2 v208, v[42:43], s[2:3] offset:512
	global_store_dwordx2 v208, v[44:45], s[2:3] offset:1024
	global_store_dwordx2 v208, v[46:47], s[2:3] offset:1536
	s_add_u32 s2, s2, 0x60000
	s_addc_u32 s3, s3, 0
	global_load_dwordx4 v[98:101], v207, s[0:1]
	global_load_dwordx4 v[102:105], v207, s[0:1] offset:1024
	global_load_dwordx4 v[106:109], v207, s[0:1] offset:2048
	global_load_dwordx4 v[110:113], v207, s[0:1] offset:3072
	s_add_u32 s0, s0, 0xc0000
	s_addc_u32 s1, s1, 0
	global_load_dwordx4 v[114:117], v207, s[0:1]
	global_load_dwordx4 v[118:121], v207, s[0:1] offset:1024
	global_load_dwordx4 v[122:125], v207, s[0:1] offset:2048
	global_load_dwordx4 v[126:129], v207, s[0:1] offset:3072
	s_add_u32 s0, s0, 0xc0000
	s_addc_u32 s1, s1, 0
	s_waitcnt vmcnt(16)
	v_mul_f32_e32 v194, v130, v130
	v_mul_f32_e32 v195, v134, v134
	v_mul_f32_e32 v196, v138, v138
	v_mul_f32_e32 v197, v142, v142
	v_mul_f32_e32 v198, v146, v146
	v_mul_f32_e32 v199, v150, v150
	v_mul_f32_e32 v200, v154, v154
	v_mul_f32_e32 v201, v158, v158
	v_fmac_f32_e32 v194, v131, v131
	v_fmac_f32_e32 v195, v135, v135
	v_fmac_f32_e32 v196, v139, v139
	v_fmac_f32_e32 v197, v143, v143
	v_fmac_f32_e32 v198, v147, v147
	v_fmac_f32_e32 v199, v151, v151
	v_fmac_f32_e32 v200, v155, v155
	v_fmac_f32_e32 v201, v159, v159
	v_fmac_f32_e32 v194, v132, v132
	v_fmac_f32_e32 v195, v136, v136
	v_fmac_f32_e32 v196, v140, v140
	v_fmac_f32_e32 v197, v144, v144
	v_fmac_f32_e32 v198, v148, v148
	v_fmac_f32_e32 v199, v152, v152
	v_fmac_f32_e32 v200, v156, v156
	v_fmac_f32_e32 v201, v160, v160
	v_fmac_f32_e32 v194, v133, v133
	v_fmac_f32_e32 v195, v137, v137
	v_fmac_f32_e32 v196, v141, v141
	v_fmac_f32_e32 v197, v145, v145
	v_fmac_f32_e32 v198, v149, v149
	v_fmac_f32_e32 v199, v153, v153
	v_fmac_f32_e32 v200, v157, v157
	v_fmac_f32_e32 v201, v161, v161
	v_add_f32_e32 v194, v194, v195
	v_add_f32_e32 v196, v196, v197
	v_add_f32_e32 v198, v198, v199
	v_add_f32_e32 v200, v200, v201
	v_add_f32_e32 v202, v194, v196
	v_add_f32_e32 v203, v198, v200
	s_nop 0
	v_add_f32_dpp v202, v202, v202 quad_perm:[1,0,3,2] row_mask:0xf bank_mask:0xf
	v_add_f32_dpp v203, v203, v203 quad_perm:[1,0,3,2] row_mask:0xf bank_mask:0xf
	s_nop 0
	v_add_f32_dpp v202, v202, v202 quad_perm:[2,3,0,1] row_mask:0xf bank_mask:0xf
	v_add_f32_dpp v203, v203, v203 quad_perm:[2,3,0,1] row_mask:0xf bank_mask:0xf
	s_nop 0
	v_add_f32_dpp v202, v202, v202 row_half_mirror row_mask:0xf bank_mask:0xf
	v_add_f32_dpp v203, v203, v203 row_half_mirror row_mask:0xf bank_mask:0xf
	s_nop 0
	v_add_f32_dpp v202, v202, v202 row_mirror row_mask:0xf bank_mask:0xf
	v_add_f32_dpp v203, v203, v203 row_mirror row_mask:0xf bank_mask:0xf
	s_nop 0
	v_add_f32_dpp v202, v202, v202 row_bcast:15 row_mask:0xa bank_mask:0xf
	v_add_f32_dpp v203, v203, v203 row_bcast:15 row_mask:0xa bank_mask:0xf
	s_nop 0
	v_add_f32_dpp v202, v202, v202 row_bcast:31 row_mask:0xc bank_mask:0xf
	v_add_f32_dpp v203, v203, v203 row_bcast:31 row_mask:0xc bank_mask:0xf
	s_nop 0
	v_fma_f32 v202, v202, s22, v206
	v_fma_f32 v203, v203, s22, v206
	v_rsq_f32_e32 v202, v202
	v_rsq_f32_e32 v203, v203
	s_nop 0
	v_readlane_b32 s10, v202, 63
	v_readlane_b32 s11, v203, 63
	s_nop 1
	v_mul_f32_e32 v204, s10, v130
	v_fma_f32 v130, v204, v162, v178
	v_mul_f32_e32 v205, s10, v131
	v_fma_f32 v131, v205, v163, v179
	v_mul_f32_e32 v204, s10, v132
	v_fma_f32 v132, v204, v164, v180
	v_mul_f32_e32 v205, s10, v133
	v_fma_f32 v133, v205, v165, v181
	v_mul_f32_e32 v204, s10, v134
	v_fma_f32 v134, v204, v166, v182
	v_mul_f32_e32 v205, s10, v135
	v_fma_f32 v135, v205, v167, v183
	v_mul_f32_e32 v204, s10, v136
	v_fma_f32 v136, v204, v168, v184
	v_mul_f32_e32 v205, s10, v137
	v_fma_f32 v137, v205, v169, v185
	v_mul_f32_e32 v204, s10, v138
	v_fma_f32 v138, v204, v170, v186
	v_mul_f32_e32 v205, s10, v139
	v_fma_f32 v139, v205, v171, v187
	v_mul_f32_e32 v204, s10, v140
	v_fma_f32 v140, v204, v172, v188
	v_mul_f32_e32 v205, s10, v141
	v_fma_f32 v141, v205, v173, v189
	v_mul_f32_e32 v204, s10, v142
	v_fma_f32 v142, v204, v174, v190
	v_mul_f32_e32 v205, s10, v143
	v_fma_f32 v143, v205, v175, v191
	v_mul_f32_e32 v204, s10, v144
	v_fma_f32 v144, v204, v176, v192
	v_mul_f32_e32 v205, s10, v145
	v_fma_f32 v145, v205, v177, v193
	v_cvt_pk_bf16_f32 v214, v130, v131
	v_cvt_pk_bf16_f32 v215, v132, v133
	v_cvt_pk_bf16_f32 v216, v134, v135
	v_cvt_pk_bf16_f32 v217, v136, v137
	v_cvt_pk_bf16_f32 v218, v138, v139
	v_cvt_pk_bf16_f32 v219, v140, v141
	v_cvt_pk_bf16_f32 v220, v142, v143
	v_cvt_pk_bf16_f32 v221, v144, v145
	global_store_dwordx2 v208, v[214:215], s[2:3]
	global_store_dwordx2 v208, v[216:217], s[2:3] offset:512
	global_store_dwordx2 v208, v[218:219], s[2:3] offset:1024
	global_store_dwordx2 v208, v[220:221], s[2:3] offset:1536
	s_add_u32 s2, s2, 0x60000
	s_addc_u32 s3, s3, 0
	v_mul_f32_e32 v204, s11, v146
	v_fma_f32 v146, v204, v162, v178
	v_mul_f32_e32 v205, s11, v147
	v_fma_f32 v147, v205, v163, v179
	v_mul_f32_e32 v204, s11, v148
	v_fma_f32 v148, v204, v164, v180
	v_mul_f32_e32 v205, s11, v149
	v_fma_f32 v149, v205, v165, v181
	v_mul_f32_e32 v204, s11, v150
	v_fma_f32 v150, v204, v166, v182
	v_mul_f32_e32 v205, s11, v151
	v_fma_f32 v151, v205, v167, v183
	v_mul_f32_e32 v204, s11, v152
	v_fma_f32 v152, v204, v168, v184
	v_mul_f32_e32 v205, s11, v153
	v_fma_f32 v153, v205, v169, v185
	v_mul_f32_e32 v204, s11, v154
	v_fma_f32 v154, v204, v170, v186
	v_mul_f32_e32 v205, s11, v155
	v_fma_f32 v155, v205, v171, v187
	v_mul_f32_e32 v204, s11, v156
	v_fma_f32 v156, v204, v172, v188
	v_mul_f32_e32 v205, s11, v157
	v_fma_f32 v157, v205, v173, v189
	v_mul_f32_e32 v204, s11, v158
	v_fma_f32 v158, v204, v174, v190
	v_mul_f32_e32 v205, s11, v159
	v_fma_f32 v159, v205, v175, v191
	v_mul_f32_e32 v204, s11, v160
	v_fma_f32 v160, v204, v176, v192
	v_mul_f32_e32 v205, s11, v161
	v_fma_f32 v161, v205, v177, v193
	v_cvt_pk_bf16_f32 v40, v146, v147
	v_cvt_pk_bf16_f32 v41, v148, v149
	v_cvt_pk_bf16_f32 v42, v150, v151
	v_cvt_pk_bf16_f32 v43, v152, v153
	v_cvt_pk_bf16_f32 v44, v154, v155
	v_cvt_pk_bf16_f32 v45, v156, v157
	v_cvt_pk_bf16_f32 v46, v158, v159
	v_cvt_pk_bf16_f32 v47, v160, v161
	global_store_dwordx2 v208, v[40:41], s[2:3]
	global_store_dwordx2 v208, v[42:43], s[2:3] offset:512
	global_store_dwordx2 v208, v[44:45], s[2:3] offset:1024
	global_store_dwordx2 v208, v[46:47], s[2:3] offset:1536
	s_add_u32 s2, s2, 0x60000
	s_addc_u32 s3, s3, 0
	global_load_dwordx4 v[130:133], v207, s[0:1]
	global_load_dwordx4 v[134:137], v207, s[0:1] offset:1024
	global_load_dwordx4 v[138:141], v207, s[0:1] offset:2048
	global_load_dwordx4 v[142:145], v207, s[0:1] offset:3072
	s_add_u32 s0, s0, 0xc0000
	s_addc_u32 s1, s1, 0
	global_load_dwordx4 v[146:149], v207, s[0:1]
	global_load_dwordx4 v[150:153], v207, s[0:1] offset:1024
	global_load_dwordx4 v[154:157], v207, s[0:1] offset:2048
	global_load_dwordx4 v[158:161], v207, s[0:1] offset:3072
	s_add_u32 s0, s0, 0xc0000
	s_addc_u32 s1, s1, 0
	s_waitcnt vmcnt(16)
	v_mul_f32_e32 v194, v98, v98
	v_mul_f32_e32 v195, v102, v102
	v_mul_f32_e32 v196, v106, v106
	v_mul_f32_e32 v197, v110, v110
	v_mul_f32_e32 v198, v114, v114
	v_mul_f32_e32 v199, v118, v118
	v_mul_f32_e32 v200, v122, v122
	v_mul_f32_e32 v201, v126, v126
	v_fmac_f32_e32 v194, v99, v99
	v_fmac_f32_e32 v195, v103, v103
	v_fmac_f32_e32 v196, v107, v107
	v_fmac_f32_e32 v197, v111, v111
	v_fmac_f32_e32 v198, v115, v115
	v_fmac_f32_e32 v199, v119, v119
	v_fmac_f32_e32 v200, v123, v123
	v_fmac_f32_e32 v201, v127, v127
	v_fmac_f32_e32 v194, v100, v100
	v_fmac_f32_e32 v195, v104, v104
	v_fmac_f32_e32 v196, v108, v108
	v_fmac_f32_e32 v197, v112, v112
	v_fmac_f32_e32 v198, v116, v116
	v_fmac_f32_e32 v199, v120, v120
	v_fmac_f32_e32 v200, v124, v124
	v_fmac_f32_e32 v201, v128, v128
	v_fmac_f32_e32 v194, v101, v101
	v_fmac_f32_e32 v195, v105, v105
	v_fmac_f32_e32 v196, v109, v109
	v_fmac_f32_e32 v197, v113, v113
	v_fmac_f32_e32 v198, v117, v117
	v_fmac_f32_e32 v199, v121, v121
	v_fmac_f32_e32 v200, v125, v125
	v_fmac_f32_e32 v201, v129, v129
	v_add_f32_e32 v194, v194, v195
	v_add_f32_e32 v196, v196, v197
	v_add_f32_e32 v198, v198, v199
	v_add_f32_e32 v200, v200, v201
	v_add_f32_e32 v202, v194, v196
	v_add_f32_e32 v203, v198, v200
	s_nop 0
	v_add_f32_dpp v202, v202, v202 quad_perm:[1,0,3,2] row_mask:0xf bank_mask:0xf
	v_add_f32_dpp v203, v203, v203 quad_perm:[1,0,3,2] row_mask:0xf bank_mask:0xf
	s_nop 0
	v_add_f32_dpp v202, v202, v202 quad_perm:[2,3,0,1] row_mask:0xf bank_mask:0xf
	v_add_f32_dpp v203, v203, v203 quad_perm:[2,3,0,1] row_mask:0xf bank_mask:0xf
	s_nop 0
	v_add_f32_dpp v202, v202, v202 row_half_mirror row_mask:0xf bank_mask:0xf
	v_add_f32_dpp v203, v203, v203 row_half_mirror row_mask:0xf bank_mask:0xf
	s_nop 0
	v_add_f32_dpp v202, v202, v202 row_mirror row_mask:0xf bank_mask:0xf
	v_add_f32_dpp v203, v203, v203 row_mirror row_mask:0xf bank_mask:0xf
	s_nop 0
	v_add_f32_dpp v202, v202, v202 row_bcast:15 row_mask:0xa bank_mask:0xf
	v_add_f32_dpp v203, v203, v203 row_bcast:15 row_mask:0xa bank_mask:0xf
	s_nop 0
	v_add_f32_dpp v202, v202, v202 row_bcast:31 row_mask:0xc bank_mask:0xf
	v_add_f32_dpp v203, v203, v203 row_bcast:31 row_mask:0xc bank_mask:0xf
	s_nop 0
	v_fma_f32 v202, v202, s22, v206
	v_fma_f32 v203, v203, s22, v206
	v_rsq_f32_e32 v202, v202
	v_rsq_f32_e32 v203, v203
	s_nop 0
	v_readlane_b32 s10, v202, 63
	v_readlane_b32 s11, v203, 63
	s_nop 1
	v_mul_f32_e32 v204, s10, v98
	v_fma_f32 v98, v204, v162, v178
	v_mul_f32_e32 v205, s10, v99
	v_fma_f32 v99, v205, v163, v179
	v_mul_f32_e32 v204, s10, v100
	v_fma_f32 v100, v204, v164, v180
	v_mul_f32_e32 v205, s10, v101
	v_fma_f32 v101, v205, v165, v181
	v_mul_f32_e32 v204, s10, v102
	v_fma_f32 v102, v204, v166, v182
	v_mul_f32_e32 v205, s10, v103
	v_fma_f32 v103, v205, v167, v183
	v_mul_f32_e32 v204, s10, v104
	v_fma_f32 v104, v204, v168, v184
	v_mul_f32_e32 v205, s10, v105
	v_fma_f32 v105, v205, v169, v185
	v_mul_f32_e32 v204, s10, v106
	v_fma_f32 v106, v204, v170, v186
	v_mul_f32_e32 v205, s10, v107
	v_fma_f32 v107, v205, v171, v187
	v_mul_f32_e32 v204, s10, v108
	v_fma_f32 v108, v204, v172, v188
	v_mul_f32_e32 v205, s10, v109
	v_fma_f32 v109, v205, v173, v189
	v_mul_f32_e32 v204, s10, v110
	v_fma_f32 v110, v204, v174, v190
	v_mul_f32_e32 v205, s10, v111
	v_fma_f32 v111, v205, v175, v191
	v_mul_f32_e32 v204, s10, v112
	v_fma_f32 v112, v204, v176, v192
	v_mul_f32_e32 v205, s10, v113
	v_fma_f32 v113, v205, v177, v193
	v_cvt_pk_bf16_f32 v214, v98, v99
	v_cvt_pk_bf16_f32 v215, v100, v101
	v_cvt_pk_bf16_f32 v216, v102, v103
	v_cvt_pk_bf16_f32 v217, v104, v105
	v_cvt_pk_bf16_f32 v218, v106, v107
	v_cvt_pk_bf16_f32 v219, v108, v109
	v_cvt_pk_bf16_f32 v220, v110, v111
	v_cvt_pk_bf16_f32 v221, v112, v113
	global_store_dwordx2 v208, v[214:215], s[2:3]
	global_store_dwordx2 v208, v[216:217], s[2:3] offset:512
	global_store_dwordx2 v208, v[218:219], s[2:3] offset:1024
	global_store_dwordx2 v208, v[220:221], s[2:3] offset:1536
	s_add_u32 s2, s2, 0x60000
	s_addc_u32 s3, s3, 0
	v_mul_f32_e32 v204, s11, v114
	v_fma_f32 v114, v204, v162, v178
	v_mul_f32_e32 v205, s11, v115
	v_fma_f32 v115, v205, v163, v179
	v_mul_f32_e32 v204, s11, v116
	v_fma_f32 v116, v204, v164, v180
	v_mul_f32_e32 v205, s11, v117
	v_fma_f32 v117, v205, v165, v181
	v_mul_f32_e32 v204, s11, v118
	v_fma_f32 v118, v204, v166, v182
	v_mul_f32_e32 v205, s11, v119
	v_fma_f32 v119, v205, v167, v183
	v_mul_f32_e32 v204, s11, v120
	v_fma_f32 v120, v204, v168, v184
	v_mul_f32_e32 v205, s11, v121
	v_fma_f32 v121, v205, v169, v185
	v_mul_f32_e32 v204, s11, v122
	v_fma_f32 v122, v204, v170, v186
	v_mul_f32_e32 v205, s11, v123
	v_fma_f32 v123, v205, v171, v187
	v_mul_f32_e32 v204, s11, v124
	v_fma_f32 v124, v204, v172, v188
	v_mul_f32_e32 v205, s11, v125
	v_fma_f32 v125, v205, v173, v189
	v_mul_f32_e32 v204, s11, v126
	v_fma_f32 v126, v204, v174, v190
	v_mul_f32_e32 v205, s11, v127
	v_fma_f32 v127, v205, v175, v191
	v_mul_f32_e32 v204, s11, v128
	v_fma_f32 v128, v204, v176, v192
	v_mul_f32_e32 v205, s11, v129
	v_fma_f32 v129, v205, v177, v193
	v_cvt_pk_bf16_f32 v40, v114, v115
	v_cvt_pk_bf16_f32 v41, v116, v117
	v_cvt_pk_bf16_f32 v42, v118, v119
	v_cvt_pk_bf16_f32 v43, v120, v121
	v_cvt_pk_bf16_f32 v44, v122, v123
	v_cvt_pk_bf16_f32 v45, v124, v125
	v_cvt_pk_bf16_f32 v46, v126, v127
	v_cvt_pk_bf16_f32 v47, v128, v129
	global_store_dwordx2 v208, v[40:41], s[2:3]
	global_store_dwordx2 v208, v[42:43], s[2:3] offset:512
	global_store_dwordx2 v208, v[44:45], s[2:3] offset:1024
	global_store_dwordx2 v208, v[46:47], s[2:3] offset:1536
	s_add_u32 s2, s2, 0x60000
	s_addc_u32 s3, s3, 0
	global_load_dwordx4 v[98:101], v207, s[0:1]
	global_load_dwordx4 v[102:105], v207, s[0:1] offset:1024
	global_load_dwordx4 v[106:109], v207, s[0:1] offset:2048
	global_load_dwordx4 v[110:113], v207, s[0:1] offset:3072
	s_add_u32 s0, s0, 0xc0000
	s_addc_u32 s1, s1, 0
	global_load_dwordx4 v[114:117], v207, s[0:1]
	global_load_dwordx4 v[118:121], v207, s[0:1] offset:1024
	global_load_dwordx4 v[122:125], v207, s[0:1] offset:2048
	global_load_dwordx4 v[126:129], v207, s[0:1] offset:3072
	s_add_u32 s0, s0, 0xc0000
	s_addc_u32 s1, s1, 0
	s_waitcnt vmcnt(16)
	v_mul_f32_e32 v194, v130, v130
	v_mul_f32_e32 v195, v134, v134
	v_mul_f32_e32 v196, v138, v138
	v_mul_f32_e32 v197, v142, v142
	v_mul_f32_e32 v198, v146, v146
	v_mul_f32_e32 v199, v150, v150
	v_mul_f32_e32 v200, v154, v154
	v_mul_f32_e32 v201, v158, v158
	v_fmac_f32_e32 v194, v131, v131
	v_fmac_f32_e32 v195, v135, v135
	v_fmac_f32_e32 v196, v139, v139
	v_fmac_f32_e32 v197, v143, v143
	v_fmac_f32_e32 v198, v147, v147
	v_fmac_f32_e32 v199, v151, v151
	v_fmac_f32_e32 v200, v155, v155
	v_fmac_f32_e32 v201, v159, v159
	v_fmac_f32_e32 v194, v132, v132
	v_fmac_f32_e32 v195, v136, v136
	v_fmac_f32_e32 v196, v140, v140
	v_fmac_f32_e32 v197, v144, v144
	v_fmac_f32_e32 v198, v148, v148
	v_fmac_f32_e32 v199, v152, v152
	v_fmac_f32_e32 v200, v156, v156
	v_fmac_f32_e32 v201, v160, v160
	v_fmac_f32_e32 v194, v133, v133
	v_fmac_f32_e32 v195, v137, v137
	v_fmac_f32_e32 v196, v141, v141
	v_fmac_f32_e32 v197, v145, v145
	v_fmac_f32_e32 v198, v149, v149
	v_fmac_f32_e32 v199, v153, v153
	v_fmac_f32_e32 v200, v157, v157
	v_fmac_f32_e32 v201, v161, v161
	v_add_f32_e32 v194, v194, v195
	v_add_f32_e32 v196, v196, v197
	v_add_f32_e32 v198, v198, v199
	v_add_f32_e32 v200, v200, v201
	v_add_f32_e32 v202, v194, v196
	v_add_f32_e32 v203, v198, v200
	s_nop 0
	v_add_f32_dpp v202, v202, v202 quad_perm:[1,0,3,2] row_mask:0xf bank_mask:0xf
	v_add_f32_dpp v203, v203, v203 quad_perm:[1,0,3,2] row_mask:0xf bank_mask:0xf
	s_nop 0
	v_add_f32_dpp v202, v202, v202 quad_perm:[2,3,0,1] row_mask:0xf bank_mask:0xf
	v_add_f32_dpp v203, v203, v203 quad_perm:[2,3,0,1] row_mask:0xf bank_mask:0xf
	s_nop 0
	v_add_f32_dpp v202, v202, v202 row_half_mirror row_mask:0xf bank_mask:0xf
	v_add_f32_dpp v203, v203, v203 row_half_mirror row_mask:0xf bank_mask:0xf
	s_nop 0
	v_add_f32_dpp v202, v202, v202 row_mirror row_mask:0xf bank_mask:0xf
	v_add_f32_dpp v203, v203, v203 row_mirror row_mask:0xf bank_mask:0xf
	s_nop 0
	v_add_f32_dpp v202, v202, v202 row_bcast:15 row_mask:0xa bank_mask:0xf
	v_add_f32_dpp v203, v203, v203 row_bcast:15 row_mask:0xa bank_mask:0xf
	s_nop 0
	v_add_f32_dpp v202, v202, v202 row_bcast:31 row_mask:0xc bank_mask:0xf
	v_add_f32_dpp v203, v203, v203 row_bcast:31 row_mask:0xc bank_mask:0xf
	s_nop 0
	v_fma_f32 v202, v202, s22, v206
	v_fma_f32 v203, v203, s22, v206
	v_rsq_f32_e32 v202, v202
	v_rsq_f32_e32 v203, v203
	s_nop 0
	v_readlane_b32 s10, v202, 63
	v_readlane_b32 s11, v203, 63
	s_nop 1
	s_cmp_lt_u32 s5, 0x80
	s_cbranch_scc1 .Ln2_r10_b0
	v_mul_f32_e32 v204, s10, v130
	v_fma_f32 v130, v204, v222, v238
	v_mul_f32_e32 v205, s10, v131
	v_fma_f32 v131, v205, v223, v239
	v_mul_f32_e32 v204, s10, v132
	v_fma_f32 v132, v204, v224, v240
	v_mul_f32_e32 v205, s10, v133
	v_fma_f32 v133, v205, v225, v241
	v_mul_f32_e32 v204, s10, v134
	v_fma_f32 v134, v204, v226, v242
	v_mul_f32_e32 v205, s10, v135
	v_fma_f32 v135, v205, v227, v243
	v_mul_f32_e32 v204, s10, v136
	v_fma_f32 v136, v204, v228, v244
	v_mul_f32_e32 v205, s10, v137
	v_fma_f32 v137, v205, v229, v245
	v_mul_f32_e32 v204, s10, v138
	v_fma_f32 v138, v204, v230, v246
	v_mul_f32_e32 v205, s10, v139
	v_fma_f32 v139, v205, v231, v247
	v_mul_f32_e32 v204, s10, v140
	v_fma_f32 v140, v204, v232, v248
	v_mul_f32_e32 v205, s10, v141
	v_fma_f32 v141, v205, v233, v249
	v_mul_f32_e32 v204, s10, v142
	v_fma_f32 v142, v204, v234, v250
	v_mul_f32_e32 v205, s10, v143
	v_fma_f32 v143, v205, v235, v251
	v_mul_f32_e32 v204, s10, v144
	v_fma_f32 v144, v204, v236, v252
	v_mul_f32_e32 v205, s10, v145
	v_fma_f32 v145, v205, v237, v253
	s_branch .Ln2_r10_done
